# v66: v63 with the GEMM main loop placed at the baseline's offset within a 64-byte line (dead-space padding only)
# baseline (speedup 1.0000x reference)
.LBB0_9:
	s_mul_i32 s3, s6, 3
	s_getpc_b64 s[0:1]
	s_add_u32 s0, s0, PROG@rel32@lo+4
	s_addc_u32 s1, s1, PROG@rel32@hi+12
	s_and_b32 s2, s3, -4
	s_add_u32 s0, s0, s2
	s_addc_u32 s1, s1, 0
	s_load_dwordx2 s[0:1], s[0:1], 0x0
	s_and_b32 s3, s3, 3
	s_lshl_b32 s3, s3, 3
	s_waitcnt lgkmcnt(0)
	s_lshr_b64 s[0:1], s[0:1], s3
	s_and_b32 s2, s0, 0xffff
	v_mov_b32_e32 v0, s2
	s_bfe_u32 s2, s0, 0x80010
	v_mov_b32_e32 v2, s2
	s_cmp_gt_u32 s6, 1
	s_cbranch_scc1 .Lsm_done
	v_readlane_b32 s0, v254, 39
	v_readlane_b32 s1, v254, 40
	s_add_u32 s0, s0, 0xc000
	s_addc_u32 s1, s1, 0
	s_cmp_eq_u32 s6, 1
	s_cbranch_scc1 .Lsm_cache
	s_getreg_b32 s2, hwreg(HW_REG_XCC_ID, 0, 4)
	s_and_b32 s2, s2, 15
	s_lshl_b32 s2, 1, s2
	s_and_b32 s3, s66, 7
	s_lshl_b32 s3, s3, 2
	s_add_u32 s0, s0, s3
	s_addc_u32 s1, s1, 0
	v_mov_b32_e32 v3, s2
	s_mov_b64 s[2:3], exec
	s_mov_b64 exec, 1
	global_atomic_or v1, v3, s[0:1]
	s_mov_b64 exec, s[2:3]
	s_branch .Lsm_done
	s_nop 0
	s_nop 0
	s_nop 0
	s_nop 0
	s_nop 0
	s_nop 0
	s_nop 0
	s_nop 0
	s_nop 0
	s_nop 0
	s_nop 0
	s_nop 0
